# speedup vs baseline: 1.0128x; 1.0050x over previous
; DEV unsigned pack2(float a, float b) { return (unsigned)f2bf(a) | ((unsigned)f2bf(b) << 16); }
; DEV void phase_scan(const Params& p, int layer) {
;     ...
;   for (long it = gtid; it < items; it += gstride) {
;     int e8 = (int)(it & 2047), dir = (int)((it >> 11) & 1), sh = (int)(it >> 12);
;     int h = sh & 3;
;     const float dec = p.dtab[((long)(layer * 4 + h) * 8 + 6) * 128 + dir];
;     float st[8];
; #pragma unroll
;     for (int i = 0; i < 8; ++i) st[i] = 0.f;
;     for (int s = 0; s < 32; ++s) {
;       int n = dir ? (31 - s) : s;
;       uint4* ptr = (uint4*)(p.KV + (((long)(sh * 32 + n)) * 2 + dir) * 16384 + e8 * 8);
;       uint4 kv = *ptr;
;       uint4 o;
;       o.x = pack2(st[0], st[1]); o.y = pack2(st[2], st[3]); o.z = pack2(st[4], st[5]); o.w = pack2(st[6], st[7]);
;       *ptr = o;
;       unsigned w4[4] = {kv.x, kv.y, kv.z, kv.w};
; #pragma unroll
;       for (int i = 0; i < 4; ++i) {
;         st[2 * i] = st[2 * i] * dec + __uint_as_float(w4[i] << 16);
;         st[2 * i + 1] = st[2 * i + 1] * dec + __uint_as_float(w4[i] & 0xffff0000u);
;       }
.LBB0_688:
	v_cndmask_b32_e64 v24, -1, 1, vcc
	s_mov_b32 s6, 0
.Lscan_b:
	v_mov_b32_e32 v22, s6
	s_sub_i32 s8, 31, s6
	v_mov_b32_e32 v21, s8
	v_cndmask_b32_e32 v25, v21, v22, vcc
	v_mad_i32_i24 v21, v24, 0, v25
	v_add_u32_e32 v22, v21, v20
	v_ashrrev_i32_e32 v23, 31, v22
	v_lshlrev_b64 v[22:23], 16, v[22:23]
	v_lshl_add_u64 v[64:65], v[4:5], 0, v[22:23]
	global_load_dwordx4 v[32:35], v[64:65], off
	v_mad_i32_i24 v21, v24, 1, v25
	v_add_u32_e32 v22, v21, v20
	v_ashrrev_i32_e32 v23, 31, v22
	v_lshlrev_b64 v[22:23], 16, v[22:23]
	v_lshl_add_u64 v[66:67], v[4:5], 0, v[22:23]
	global_load_dwordx4 v[36:39], v[66:67], off
	v_mad_i32_i24 v21, v24, 2, v25
	v_add_u32_e32 v22, v21, v20
	v_ashrrev_i32_e32 v23, 31, v22
	v_lshlrev_b64 v[22:23], 16, v[22:23]
	v_lshl_add_u64 v[68:69], v[4:5], 0, v[22:23]
	global_load_dwordx4 v[40:43], v[68:69], off
	v_mad_i32_i24 v21, v24, 3, v25
	v_add_u32_e32 v22, v21, v20
	v_ashrrev_i32_e32 v23, 31, v22
	v_lshlrev_b64 v[22:23], 16, v[22:23]
	v_lshl_add_u64 v[70:71], v[4:5], 0, v[22:23]
	global_load_dwordx4 v[44:47], v[70:71], off
	v_mad_i32_i24 v21, v24, 4, v25
	v_add_u32_e32 v22, v21, v20
	v_ashrrev_i32_e32 v23, 31, v22
	v_lshlrev_b64 v[22:23], 16, v[22:23]
	v_lshl_add_u64 v[72:73], v[4:5], 0, v[22:23]
	global_load_dwordx4 v[48:51], v[72:73], off
	v_mad_i32_i24 v21, v24, 5, v25
	v_add_u32_e32 v22, v21, v20
	v_ashrrev_i32_e32 v23, 31, v22
	v_lshlrev_b64 v[22:23], 16, v[22:23]
	v_lshl_add_u64 v[74:75], v[4:5], 0, v[22:23]
	global_load_dwordx4 v[52:55], v[74:75], off
	v_mad_i32_i24 v21, v24, 6, v25
	v_add_u32_e32 v22, v21, v20
	v_ashrrev_i32_e32 v23, 31, v22
	v_lshlrev_b64 v[22:23], 16, v[22:23]
	v_lshl_add_u64 v[76:77], v[4:5], 0, v[22:23]
	global_load_dwordx4 v[56:59], v[76:77], off
	v_mad_i32_i24 v21, v24, 7, v25
	v_add_u32_e32 v22, v21, v20
	v_ashrrev_i32_e32 v23, 31, v22
	v_lshlrev_b64 v[22:23], 16, v[22:23]
	v_lshl_add_u64 v[78:79], v[4:5], 0, v[22:23]
	global_load_dwordx4 v[60:63], v[78:79], off
	s_waitcnt vmcnt(0)
	v_and_b32_sdwa v80, v13, v172 dst_sel:DWORD dst_unused:UNUSED_PAD src0_sel:WORD_1 src1_sel:DWORD
	v_and_b32_sdwa v81, v12, v172 dst_sel:DWORD dst_unused:UNUSED_PAD src0_sel:WORD_1 src1_sel:DWORD
	v_add3_u32 v80, v13, v80, s86
	v_add3_u32 v81, v12, v81, s86
	v_and_b32_e32 v80, 0xffff0000, v80
	v_or_b32_sdwa v84, v80, v81 dst_sel:DWORD dst_unused:UNUSED_PAD src0_sel:DWORD src1_sel:WORD_1
	v_and_b32_sdwa v80, v15, v172 dst_sel:DWORD dst_unused:UNUSED_PAD src0_sel:WORD_1 src1_sel:DWORD
	v_and_b32_sdwa v81, v14, v172 dst_sel:DWORD dst_unused:UNUSED_PAD src0_sel:WORD_1 src1_sel:DWORD
	v_add3_u32 v80, v15, v80, s86
	v_add3_u32 v81, v14, v81, s86
	v_and_b32_e32 v80, 0xffff0000, v80
	v_or_b32_sdwa v85, v80, v81 dst_sel:DWORD dst_unused:UNUSED_PAD src0_sel:DWORD src1_sel:WORD_1
	v_and_b32_sdwa v80, v17, v172 dst_sel:DWORD dst_unused:UNUSED_PAD src0_sel:WORD_1 src1_sel:DWORD
	v_and_b32_sdwa v81, v16, v172 dst_sel:DWORD dst_unused:UNUSED_PAD src0_sel:WORD_1 src1_sel:DWORD
	v_add3_u32 v80, v17, v80, s86
	v_add3_u32 v81, v16, v81, s86
	v_and_b32_e32 v80, 0xffff0000, v80
	v_or_b32_sdwa v86, v80, v81 dst_sel:DWORD dst_unused:UNUSED_PAD src0_sel:DWORD src1_sel:WORD_1
	v_and_b32_sdwa v80, v19, v172 dst_sel:DWORD dst_unused:UNUSED_PAD src0_sel:WORD_1 src1_sel:DWORD
	v_and_b32_sdwa v81, v18, v172 dst_sel:DWORD dst_unused:UNUSED_PAD src0_sel:WORD_1 src1_sel:DWORD
	v_add3_u32 v80, v19, v80, s86
	v_add3_u32 v81, v18, v81, s86
	v_and_b32_e32 v80, 0xffff0000, v80
	v_or_b32_sdwa v87, v80, v81 dst_sel:DWORD dst_unused:UNUSED_PAD src0_sel:DWORD src1_sel:WORD_1
	global_store_dwordx4 v[64:65], v[84:87], off
	v_lshlrev_b32_e32 v82, 16, v32
	v_and_b32_e32 v83, 0xffff0000, v32
	v_pk_fma_f32 v[12:13], v[2:3], v[12:13], v[82:83]
	v_lshlrev_b32_e32 v82, 16, v33
	v_and_b32_e32 v83, 0xffff0000, v33
	v_pk_fma_f32 v[14:15], v[2:3], v[14:15], v[82:83]
	v_lshlrev_b32_e32 v82, 16, v34
	v_and_b32_e32 v83, 0xffff0000, v34
	v_pk_fma_f32 v[16:17], v[2:3], v[16:17], v[82:83]
	v_lshlrev_b32_e32 v82, 16, v35
	v_and_b32_e32 v83, 0xffff0000, v35
	v_pk_fma_f32 v[18:19], v[2:3], v[18:19], v[82:83]
	v_and_b32_sdwa v80, v13, v172 dst_sel:DWORD dst_unused:UNUSED_PAD src0_sel:WORD_1 src1_sel:DWORD
	v_and_b32_sdwa v81, v12, v172 dst_sel:DWORD dst_unused:UNUSED_PAD src0_sel:WORD_1 src1_sel:DWORD
	v_add3_u32 v80, v13, v80, s86
	v_add3_u32 v81, v12, v81, s86
	v_and_b32_e32 v80, 0xffff0000, v80
	v_or_b32_sdwa v88, v80, v81 dst_sel:DWORD dst_unused:UNUSED_PAD src0_sel:DWORD src1_sel:WORD_1
	v_and_b32_sdwa v80, v15, v172 dst_sel:DWORD dst_unused:UNUSED_PAD src0_sel:WORD_1 src1_sel:DWORD
	v_and_b32_sdwa v81, v14, v172 dst_sel:DWORD dst_unused:UNUSED_PAD src0_sel:WORD_1 src1_sel:DWORD
	v_add3_u32 v80, v15, v80, s86
	v_add3_u32 v81, v14, v81, s86
	v_and_b32_e32 v80, 0xffff0000, v80
	v_or_b32_sdwa v89, v80, v81 dst_sel:DWORD dst_unused:UNUSED_PAD src0_sel:DWORD src1_sel:WORD_1
	v_and_b32_sdwa v80, v17, v172 dst_sel:DWORD dst_unused:UNUSED_PAD src0_sel:WORD_1 src1_sel:DWORD
	v_and_b32_sdwa v81, v16, v172 dst_sel:DWORD dst_unused:UNUSED_PAD src0_sel:WORD_1 src1_sel:DWORD
	v_add3_u32 v80, v17, v80, s86
	v_add3_u32 v81, v16, v81, s86
	v_and_b32_e32 v80, 0xffff0000, v80
	v_or_b32_sdwa v90, v80, v81 dst_sel:DWORD dst_unused:UNUSED_PAD src0_sel:DWORD src1_sel:WORD_1
	v_and_b32_sdwa v80, v19, v172 dst_sel:DWORD dst_unused:UNUSED_PAD src0_sel:WORD_1 src1_sel:DWORD
	v_and_b32_sdwa v81, v18, v172 dst_sel:DWORD dst_unused:UNUSED_PAD src0_sel:WORD_1 src1_sel:DWORD
	v_add3_u32 v80, v19, v80, s86
	v_add3_u32 v81, v18, v81, s86
	v_and_b32_e32 v80, 0xffff0000, v80
	v_or_b32_sdwa v91, v80, v81 dst_sel:DWORD dst_unused:UNUSED_PAD src0_sel:DWORD src1_sel:WORD_1
; DEV unsigned pack2(float a, float b) { return (unsigned)f2bf(a) | ((unsigned)f2bf(b) << 16); }
; DEV void phase_scan(const Params& p, int layer) {
;     ...
;     for (int s = 0; s < 32; ++s) {
;       int n = dir ? (31 - s) : s;
;       uint4* ptr = (uint4*)(p.KV + (((long)(sh * 32 + n)) * 2 + dir) * 16384 + e8 * 8);
;       uint4 kv = *ptr;
;       uint4 o;
;       o.x = pack2(st[0], st[1]); o.y = pack2(st[2], st[3]); o.z = pack2(st[4], st[5]); o.w = pack2(st[6], st[7]);
;       *ptr = o;
;       unsigned w4[4] = {kv.x, kv.y, kv.z, kv.w};
; #pragma unroll
;       for (int i = 0; i < 4; ++i) {
;         st[2 * i] = st[2 * i] * dec + __uint_as_float(w4[i] << 16);
;         st[2 * i + 1] = st[2 * i + 1] * dec + __uint_as_float(w4[i] & 0xffff0000u);
;       }
	global_store_dwordx4 v[66:67], v[88:91], off
	v_lshlrev_b32_e32 v82, 16, v36
	v_and_b32_e32 v83, 0xffff0000, v36
	v_pk_fma_f32 v[12:13], v[2:3], v[12:13], v[82:83]
	v_lshlrev_b32_e32 v82, 16, v37
	v_and_b32_e32 v83, 0xffff0000, v37
	v_pk_fma_f32 v[14:15], v[2:3], v[14:15], v[82:83]
	v_lshlrev_b32_e32 v82, 16, v38
	v_and_b32_e32 v83, 0xffff0000, v38
	v_pk_fma_f32 v[16:17], v[2:3], v[16:17], v[82:83]
	v_lshlrev_b32_e32 v82, 16, v39
	v_and_b32_e32 v83, 0xffff0000, v39
	v_pk_fma_f32 v[18:19], v[2:3], v[18:19], v[82:83]
	v_and_b32_sdwa v80, v13, v172 dst_sel:DWORD dst_unused:UNUSED_PAD src0_sel:WORD_1 src1_sel:DWORD
	v_and_b32_sdwa v81, v12, v172 dst_sel:DWORD dst_unused:UNUSED_PAD src0_sel:WORD_1 src1_sel:DWORD
	v_add3_u32 v80, v13, v80, s86
	v_add3_u32 v81, v12, v81, s86
	v_and_b32_e32 v80, 0xffff0000, v80
	v_or_b32_sdwa v84, v80, v81 dst_sel:DWORD dst_unused:UNUSED_PAD src0_sel:DWORD src1_sel:WORD_1
	v_and_b32_sdwa v80, v15, v172 dst_sel:DWORD dst_unused:UNUSED_PAD src0_sel:WORD_1 src1_sel:DWORD
	v_and_b32_sdwa v81, v14, v172 dst_sel:DWORD dst_unused:UNUSED_PAD src0_sel:WORD_1 src1_sel:DWORD
	v_add3_u32 v80, v15, v80, s86
	v_add3_u32 v81, v14, v81, s86
	v_and_b32_e32 v80, 0xffff0000, v80
	v_or_b32_sdwa v85, v80, v81 dst_sel:DWORD dst_unused:UNUSED_PAD src0_sel:DWORD src1_sel:WORD_1
	v_and_b32_sdwa v80, v17, v172 dst_sel:DWORD dst_unused:UNUSED_PAD src0_sel:WORD_1 src1_sel:DWORD
	v_and_b32_sdwa v81, v16, v172 dst_sel:DWORD dst_unused:UNUSED_PAD src0_sel:WORD_1 src1_sel:DWORD
	v_add3_u32 v80, v17, v80, s86
	v_add3_u32 v81, v16, v81, s86
	v_and_b32_e32 v80, 0xffff0000, v80
	v_or_b32_sdwa v86, v80, v81 dst_sel:DWORD dst_unused:UNUSED_PAD src0_sel:DWORD src1_sel:WORD_1
	v_and_b32_sdwa v80, v19, v172 dst_sel:DWORD dst_unused:UNUSED_PAD src0_sel:WORD_1 src1_sel:DWORD
	v_and_b32_sdwa v81, v18, v172 dst_sel:DWORD dst_unused:UNUSED_PAD src0_sel:WORD_1 src1_sel:DWORD
	v_add3_u32 v80, v19, v80, s86
	v_add3_u32 v81, v18, v81, s86
	v_and_b32_e32 v80, 0xffff0000, v80
	v_or_b32_sdwa v87, v80, v81 dst_sel:DWORD dst_unused:UNUSED_PAD src0_sel:DWORD src1_sel:WORD_1
	global_store_dwordx4 v[68:69], v[84:87], off
	v_lshlrev_b32_e32 v82, 16, v40
	v_and_b32_e32 v83, 0xffff0000, v40
	v_pk_fma_f32 v[12:13], v[2:3], v[12:13], v[82:83]
	v_lshlrev_b32_e32 v82, 16, v41
	v_and_b32_e32 v83, 0xffff0000, v41
	v_pk_fma_f32 v[14:15], v[2:3], v[14:15], v[82:83]
	v_lshlrev_b32_e32 v82, 16, v42
	v_and_b32_e32 v83, 0xffff0000, v42
	v_pk_fma_f32 v[16:17], v[2:3], v[16:17], v[82:83]
	v_lshlrev_b32_e32 v82, 16, v43
	v_and_b32_e32 v83, 0xffff0000, v43
	v_pk_fma_f32 v[18:19], v[2:3], v[18:19], v[82:83]
	v_and_b32_sdwa v80, v13, v172 dst_sel:DWORD dst_unused:UNUSED_PAD src0_sel:WORD_1 src1_sel:DWORD
	v_and_b32_sdwa v81, v12, v172 dst_sel:DWORD dst_unused:UNUSED_PAD src0_sel:WORD_1 src1_sel:DWORD
	v_add3_u32 v80, v13, v80, s86
	v_add3_u32 v81, v12, v81, s86
	v_and_b32_e32 v80, 0xffff0000, v80
	v_or_b32_sdwa v88, v80, v81 dst_sel:DWORD dst_unused:UNUSED_PAD src0_sel:DWORD src1_sel:WORD_1
	v_and_b32_sdwa v80, v15, v172 dst_sel:DWORD dst_unused:UNUSED_PAD src0_sel:WORD_1 src1_sel:DWORD
	v_and_b32_sdwa v81, v14, v172 dst_sel:DWORD dst_unused:UNUSED_PAD src0_sel:WORD_1 src1_sel:DWORD
	v_add3_u32 v80, v15, v80, s86
	v_add3_u32 v81, v14, v81, s86
	v_and_b32_e32 v80, 0xffff0000, v80
	v_or_b32_sdwa v89, v80, v81 dst_sel:DWORD dst_unused:UNUSED_PAD src0_sel:DWORD src1_sel:WORD_1
	v_and_b32_sdwa v80, v17, v172 dst_sel:DWORD dst_unused:UNUSED_PAD src0_sel:WORD_1 src1_sel:DWORD
	v_and_b32_sdwa v81, v16, v172 dst_sel:DWORD dst_unused:UNUSED_PAD src0_sel:WORD_1 src1_sel:DWORD
	v_add3_u32 v80, v17, v80, s86
	v_add3_u32 v81, v16, v81, s86
	v_and_b32_e32 v80, 0xffff0000, v80
	v_or_b32_sdwa v90, v80, v81 dst_sel:DWORD dst_unused:UNUSED_PAD src0_sel:DWORD src1_sel:WORD_1
	v_and_b32_sdwa v80, v19, v172 dst_sel:DWORD dst_unused:UNUSED_PAD src0_sel:WORD_1 src1_sel:DWORD
	v_and_b32_sdwa v81, v18, v172 dst_sel:DWORD dst_unused:UNUSED_PAD src0_sel:WORD_1 src1_sel:DWORD
	v_add3_u32 v80, v19, v80, s86
	v_add3_u32 v81, v18, v81, s86
	v_and_b32_e32 v80, 0xffff0000, v80
	v_or_b32_sdwa v91, v80, v81 dst_sel:DWORD dst_unused:UNUSED_PAD src0_sel:DWORD src1_sel:WORD_1
	global_store_dwordx4 v[70:71], v[88:91], off
	v_lshlrev_b32_e32 v82, 16, v44
	v_and_b32_e32 v83, 0xffff0000, v44
	v_pk_fma_f32 v[12:13], v[2:3], v[12:13], v[82:83]
	v_lshlrev_b32_e32 v82, 16, v45
	v_and_b32_e32 v83, 0xffff0000, v45
	v_pk_fma_f32 v[14:15], v[2:3], v[14:15], v[82:83]
	v_lshlrev_b32_e32 v82, 16, v46
	v_and_b32_e32 v83, 0xffff0000, v46
	v_pk_fma_f32 v[16:17], v[2:3], v[16:17], v[82:83]
	v_lshlrev_b32_e32 v82, 16, v47
	v_and_b32_e32 v83, 0xffff0000, v47
	v_pk_fma_f32 v[18:19], v[2:3], v[18:19], v[82:83]
	v_and_b32_sdwa v80, v13, v172 dst_sel:DWORD dst_unused:UNUSED_PAD src0_sel:WORD_1 src1_sel:DWORD
	v_and_b32_sdwa v81, v12, v172 dst_sel:DWORD dst_unused:UNUSED_PAD src0_sel:WORD_1 src1_sel:DWORD
	v_add3_u32 v80, v13, v80, s86
	v_add3_u32 v81, v12, v81, s86
	v_and_b32_e32 v80, 0xffff0000, v80
	v_or_b32_sdwa v84, v80, v81 dst_sel:DWORD dst_unused:UNUSED_PAD src0_sel:DWORD src1_sel:WORD_1
	v_and_b32_sdwa v80, v15, v172 dst_sel:DWORD dst_unused:UNUSED_PAD src0_sel:WORD_1 src1_sel:DWORD
	v_and_b32_sdwa v81, v14, v172 dst_sel:DWORD dst_unused:UNUSED_PAD src0_sel:WORD_1 src1_sel:DWORD
	v_add3_u32 v80, v15, v80, s86
	v_add3_u32 v81, v14, v81, s86
	v_and_b32_e32 v80, 0xffff0000, v80
	v_or_b32_sdwa v85, v80, v81 dst_sel:DWORD dst_unused:UNUSED_PAD src0_sel:DWORD src1_sel:WORD_1
	v_and_b32_sdwa v80, v17, v172 dst_sel:DWORD dst_unused:UNUSED_PAD src0_sel:WORD_1 src1_sel:DWORD
	v_and_b32_sdwa v81, v16, v172 dst_sel:DWORD dst_unused:UNUSED_PAD src0_sel:WORD_1 src1_sel:DWORD
; DEV unsigned pack2(float a, float b) { return (unsigned)f2bf(a) | ((unsigned)f2bf(b) << 16); }
; DEV void phase_scan(const Params& p, int layer) {
;     ...
;     for (int s = 0; s < 32; ++s) {
;       int n = dir ? (31 - s) : s;
;       uint4* ptr = (uint4*)(p.KV + (((long)(sh * 32 + n)) * 2 + dir) * 16384 + e8 * 8);
;       uint4 kv = *ptr;
;       uint4 o;
;       o.x = pack2(st[0], st[1]); o.y = pack2(st[2], st[3]); o.z = pack2(st[4], st[5]); o.w = pack2(st[6], st[7]);
;       *ptr = o;
;       unsigned w4[4] = {kv.x, kv.y, kv.z, kv.w};
; #pragma unroll
;       for (int i = 0; i < 4; ++i) {
;         st[2 * i] = st[2 * i] * dec + __uint_as_float(w4[i] << 16);
;         st[2 * i + 1] = st[2 * i + 1] * dec + __uint_as_float(w4[i] & 0xffff0000u);
;       }
	v_add3_u32 v80, v17, v80, s86
	v_add3_u32 v81, v16, v81, s86
	v_and_b32_e32 v80, 0xffff0000, v80
	v_or_b32_sdwa v86, v80, v81 dst_sel:DWORD dst_unused:UNUSED_PAD src0_sel:DWORD src1_sel:WORD_1
	v_and_b32_sdwa v80, v19, v172 dst_sel:DWORD dst_unused:UNUSED_PAD src0_sel:WORD_1 src1_sel:DWORD
	v_and_b32_sdwa v81, v18, v172 dst_sel:DWORD dst_unused:UNUSED_PAD src0_sel:WORD_1 src1_sel:DWORD
	v_add3_u32 v80, v19, v80, s86
	v_add3_u32 v81, v18, v81, s86
	v_and_b32_e32 v80, 0xffff0000, v80
	v_or_b32_sdwa v87, v80, v81 dst_sel:DWORD dst_unused:UNUSED_PAD src0_sel:DWORD src1_sel:WORD_1
	global_store_dwordx4 v[72:73], v[84:87], off
	v_lshlrev_b32_e32 v82, 16, v48
	v_and_b32_e32 v83, 0xffff0000, v48
	v_pk_fma_f32 v[12:13], v[2:3], v[12:13], v[82:83]
	v_lshlrev_b32_e32 v82, 16, v49
	v_and_b32_e32 v83, 0xffff0000, v49
	v_pk_fma_f32 v[14:15], v[2:3], v[14:15], v[82:83]
	v_lshlrev_b32_e32 v82, 16, v50
	v_and_b32_e32 v83, 0xffff0000, v50
	v_pk_fma_f32 v[16:17], v[2:3], v[16:17], v[82:83]
	v_lshlrev_b32_e32 v82, 16, v51
	v_and_b32_e32 v83, 0xffff0000, v51
	v_pk_fma_f32 v[18:19], v[2:3], v[18:19], v[82:83]
	v_and_b32_sdwa v80, v13, v172 dst_sel:DWORD dst_unused:UNUSED_PAD src0_sel:WORD_1 src1_sel:DWORD
	v_and_b32_sdwa v81, v12, v172 dst_sel:DWORD dst_unused:UNUSED_PAD src0_sel:WORD_1 src1_sel:DWORD
	v_add3_u32 v80, v13, v80, s86
	v_add3_u32 v81, v12, v81, s86
	v_and_b32_e32 v80, 0xffff0000, v80
	v_or_b32_sdwa v88, v80, v81 dst_sel:DWORD dst_unused:UNUSED_PAD src0_sel:DWORD src1_sel:WORD_1
	v_and_b32_sdwa v80, v15, v172 dst_sel:DWORD dst_unused:UNUSED_PAD src0_sel:WORD_1 src1_sel:DWORD
	v_and_b32_sdwa v81, v14, v172 dst_sel:DWORD dst_unused:UNUSED_PAD src0_sel:WORD_1 src1_sel:DWORD
	v_add3_u32 v80, v15, v80, s86
	v_add3_u32 v81, v14, v81, s86
	v_and_b32_e32 v80, 0xffff0000, v80
	v_or_b32_sdwa v89, v80, v81 dst_sel:DWORD dst_unused:UNUSED_PAD src0_sel:DWORD src1_sel:WORD_1
	v_and_b32_sdwa v80, v17, v172 dst_sel:DWORD dst_unused:UNUSED_PAD src0_sel:WORD_1 src1_sel:DWORD
	v_and_b32_sdwa v81, v16, v172 dst_sel:DWORD dst_unused:UNUSED_PAD src0_sel:WORD_1 src1_sel:DWORD
	v_add3_u32 v80, v17, v80, s86
	v_add3_u32 v81, v16, v81, s86
	v_and_b32_e32 v80, 0xffff0000, v80
	v_or_b32_sdwa v90, v80, v81 dst_sel:DWORD dst_unused:UNUSED_PAD src0_sel:DWORD src1_sel:WORD_1
	v_and_b32_sdwa v80, v19, v172 dst_sel:DWORD dst_unused:UNUSED_PAD src0_sel:WORD_1 src1_sel:DWORD
	v_and_b32_sdwa v81, v18, v172 dst_sel:DWORD dst_unused:UNUSED_PAD src0_sel:WORD_1 src1_sel:DWORD
	v_add3_u32 v80, v19, v80, s86
	v_add3_u32 v81, v18, v81, s86
	v_and_b32_e32 v80, 0xffff0000, v80
	v_or_b32_sdwa v91, v80, v81 dst_sel:DWORD dst_unused:UNUSED_PAD src0_sel:DWORD src1_sel:WORD_1
	global_store_dwordx4 v[74:75], v[88:91], off
	v_lshlrev_b32_e32 v82, 16, v52
	v_and_b32_e32 v83, 0xffff0000, v52
	v_pk_fma_f32 v[12:13], v[2:3], v[12:13], v[82:83]
	v_lshlrev_b32_e32 v82, 16, v53
	v_and_b32_e32 v83, 0xffff0000, v53
	v_pk_fma_f32 v[14:15], v[2:3], v[14:15], v[82:83]
	v_lshlrev_b32_e32 v82, 16, v54
	v_and_b32_e32 v83, 0xffff0000, v54
	v_pk_fma_f32 v[16:17], v[2:3], v[16:17], v[82:83]
	v_lshlrev_b32_e32 v82, 16, v55
	v_and_b32_e32 v83, 0xffff0000, v55
	v_pk_fma_f32 v[18:19], v[2:3], v[18:19], v[82:83]
	v_and_b32_sdwa v80, v13, v172 dst_sel:DWORD dst_unused:UNUSED_PAD src0_sel:WORD_1 src1_sel:DWORD
	v_and_b32_sdwa v81, v12, v172 dst_sel:DWORD dst_unused:UNUSED_PAD src0_sel:WORD_1 src1_sel:DWORD
	v_add3_u32 v80, v13, v80, s86
	v_add3_u32 v81, v12, v81, s86
	v_and_b32_e32 v80, 0xffff0000, v80
	v_or_b32_sdwa v84, v80, v81 dst_sel:DWORD dst_unused:UNUSED_PAD src0_sel:DWORD src1_sel:WORD_1
	v_and_b32_sdwa v80, v15, v172 dst_sel:DWORD dst_unused:UNUSED_PAD src0_sel:WORD_1 src1_sel:DWORD
	v_and_b32_sdwa v81, v14, v172 dst_sel:DWORD dst_unused:UNUSED_PAD src0_sel:WORD_1 src1_sel:DWORD
	v_add3_u32 v80, v15, v80, s86
; DEV unsigned pack2(float a, float b) { return (unsigned)f2bf(a) | ((unsigned)f2bf(b) << 16); }
; DEV void phase_scan(const Params& p, int layer) {
;     ...
;   for (long it = gtid; it < items; it += gstride) {
;     int e8 = (int)(it & 2047), dir = (int)((it >> 11) & 1), sh = (int)(it >> 12);
;     int h = sh & 3;
;     const float dec = p.dtab[((long)(layer * 4 + h) * 8 + 6) * 128 + dir];
;     float st[8];
; #pragma unroll
;     for (int i = 0; i < 8; ++i) st[i] = 0.f;
;     for (int s = 0; s < 32; ++s) {
;       int n = dir ? (31 - s) : s;
;       uint4* ptr = (uint4*)(p.KV + (((long)(sh * 32 + n)) * 2 + dir) * 16384 + e8 * 8);
;       uint4 kv = *ptr;
;       uint4 o;
;       o.x = pack2(st[0], st[1]); o.y = pack2(st[2], st[3]); o.z = pack2(st[4], st[5]); o.w = pack2(st[6], st[7]);
;       *ptr = o;
;       unsigned w4[4] = {kv.x, kv.y, kv.z, kv.w};
; #pragma unroll
;       for (int i = 0; i < 4; ++i) {
;         st[2 * i] = st[2 * i] * dec + __uint_as_float(w4[i] << 16);
;         st[2 * i + 1] = st[2 * i + 1] * dec + __uint_as_float(w4[i] & 0xffff0000u);
;       }
;     }
;   }
	v_add3_u32 v81, v14, v81, s86
	v_and_b32_e32 v80, 0xffff0000, v80
	v_or_b32_sdwa v85, v80, v81 dst_sel:DWORD dst_unused:UNUSED_PAD src0_sel:DWORD src1_sel:WORD_1
	v_and_b32_sdwa v80, v17, v172 dst_sel:DWORD dst_unused:UNUSED_PAD src0_sel:WORD_1 src1_sel:DWORD
	v_and_b32_sdwa v81, v16, v172 dst_sel:DWORD dst_unused:UNUSED_PAD src0_sel:WORD_1 src1_sel:DWORD
	v_add3_u32 v80, v17, v80, s86
	v_add3_u32 v81, v16, v81, s86
	v_and_b32_e32 v80, 0xffff0000, v80
	v_or_b32_sdwa v86, v80, v81 dst_sel:DWORD dst_unused:UNUSED_PAD src0_sel:DWORD src1_sel:WORD_1
	v_and_b32_sdwa v80, v19, v172 dst_sel:DWORD dst_unused:UNUSED_PAD src0_sel:WORD_1 src1_sel:DWORD
	v_and_b32_sdwa v81, v18, v172 dst_sel:DWORD dst_unused:UNUSED_PAD src0_sel:WORD_1 src1_sel:DWORD
	v_add3_u32 v80, v19, v80, s86
	v_add3_u32 v81, v18, v81, s86
	v_and_b32_e32 v80, 0xffff0000, v80
	v_or_b32_sdwa v87, v80, v81 dst_sel:DWORD dst_unused:UNUSED_PAD src0_sel:DWORD src1_sel:WORD_1
	global_store_dwordx4 v[76:77], v[84:87], off
	v_lshlrev_b32_e32 v82, 16, v56
	v_and_b32_e32 v83, 0xffff0000, v56
	v_pk_fma_f32 v[12:13], v[2:3], v[12:13], v[82:83]
	v_lshlrev_b32_e32 v82, 16, v57
	v_and_b32_e32 v83, 0xffff0000, v57
	v_pk_fma_f32 v[14:15], v[2:3], v[14:15], v[82:83]
	v_lshlrev_b32_e32 v82, 16, v58
	v_and_b32_e32 v83, 0xffff0000, v58
	v_pk_fma_f32 v[16:17], v[2:3], v[16:17], v[82:83]
	v_lshlrev_b32_e32 v82, 16, v59
	v_and_b32_e32 v83, 0xffff0000, v59
	v_pk_fma_f32 v[18:19], v[2:3], v[18:19], v[82:83]
	v_and_b32_sdwa v80, v13, v172 dst_sel:DWORD dst_unused:UNUSED_PAD src0_sel:WORD_1 src1_sel:DWORD
	v_and_b32_sdwa v81, v12, v172 dst_sel:DWORD dst_unused:UNUSED_PAD src0_sel:WORD_1 src1_sel:DWORD
	v_add3_u32 v80, v13, v80, s86
	v_add3_u32 v81, v12, v81, s86
	v_and_b32_e32 v80, 0xffff0000, v80
	v_or_b32_sdwa v88, v80, v81 dst_sel:DWORD dst_unused:UNUSED_PAD src0_sel:DWORD src1_sel:WORD_1
	v_and_b32_sdwa v80, v15, v172 dst_sel:DWORD dst_unused:UNUSED_PAD src0_sel:WORD_1 src1_sel:DWORD
	v_and_b32_sdwa v81, v14, v172 dst_sel:DWORD dst_unused:UNUSED_PAD src0_sel:WORD_1 src1_sel:DWORD
	v_add3_u32 v80, v15, v80, s86
	v_add3_u32 v81, v14, v81, s86
	v_and_b32_e32 v80, 0xffff0000, v80
	v_or_b32_sdwa v89, v80, v81 dst_sel:DWORD dst_unused:UNUSED_PAD src0_sel:DWORD src1_sel:WORD_1
	v_and_b32_sdwa v80, v17, v172 dst_sel:DWORD dst_unused:UNUSED_PAD src0_sel:WORD_1 src1_sel:DWORD
	v_and_b32_sdwa v81, v16, v172 dst_sel:DWORD dst_unused:UNUSED_PAD src0_sel:WORD_1 src1_sel:DWORD
	v_add3_u32 v80, v17, v80, s86
	v_add3_u32 v81, v16, v81, s86
	v_and_b32_e32 v80, 0xffff0000, v80
	v_or_b32_sdwa v90, v80, v81 dst_sel:DWORD dst_unused:UNUSED_PAD src0_sel:DWORD src1_sel:WORD_1
	v_and_b32_sdwa v80, v19, v172 dst_sel:DWORD dst_unused:UNUSED_PAD src0_sel:WORD_1 src1_sel:DWORD
	v_and_b32_sdwa v81, v18, v172 dst_sel:DWORD dst_unused:UNUSED_PAD src0_sel:WORD_1 src1_sel:DWORD
	v_add3_u32 v80, v19, v80, s86
	v_add3_u32 v81, v18, v81, s86
	v_and_b32_e32 v80, 0xffff0000, v80
	v_or_b32_sdwa v91, v80, v81 dst_sel:DWORD dst_unused:UNUSED_PAD src0_sel:DWORD src1_sel:WORD_1
	global_store_dwordx4 v[78:79], v[88:91], off
	v_lshlrev_b32_e32 v82, 16, v60
	v_and_b32_e32 v83, 0xffff0000, v60
	v_pk_fma_f32 v[12:13], v[2:3], v[12:13], v[82:83]
	v_lshlrev_b32_e32 v82, 16, v61
	v_and_b32_e32 v83, 0xffff0000, v61
	v_pk_fma_f32 v[14:15], v[2:3], v[14:15], v[82:83]
	v_lshlrev_b32_e32 v82, 16, v62
	v_and_b32_e32 v83, 0xffff0000, v62
	v_pk_fma_f32 v[16:17], v[2:3], v[16:17], v[82:83]
	v_lshlrev_b32_e32 v82, 16, v63
	v_and_b32_e32 v83, 0xffff0000, v63
	v_pk_fma_f32 v[18:19], v[2:3], v[18:19], v[82:83]
	s_add_i32 s6, s6, 8
	s_cmp_lt_u32 s6, 32
	s_cbranch_scc1 .Lscan_b
	v_lshl_add_u64 v[0:1], v[0:1], 0, s[2:3]
	s_mov_b64 s[6:7], 0x27fff
	v_cmp_lt_i64_e32 vcc, s[6:7], v[0:1]
	s_or_b64 s[4:5], vcc, s[4:5]
	s_andn2_b64 exec, exec, s[4:5]
	s_cbranch_execnz .LBB0_687
